# attention epilogue: 16 row-per-lane dwordx2 stores widened to 8 dwordx4 stores with v_permlane32_swap pairs
# speedup vs baseline: 1.0046x; 1.0046x over previous
.LBB0_446:
	s_andn2_b64 vcc, exec, s[4:5]
	s_waitcnt lgkmcnt(0)
	s_barrier
	s_cbranch_vccnz .LBB0_427
	ds_read2st64_b32 v[26:27], v24 offset1:1
	ds_read2st64_b32 v[28:29], v24 offset0:2 offset1:3
	ds_read2st64_b32 v[30:31], v24 offset0:4 offset1:5
	ds_read2st64_b32 v[46:47], v24 offset0:6 offset1:7
	ds_read2st64_b32 v[62:63], v24 offset0:8 offset1:9
	ds_read2st64_b32 v[96:97], v24 offset0:10 offset1:11
	ds_read2st64_b32 v[98:99], v24 offset0:12 offset1:13
	ds_read2st64_b32 v[100:101], v24 offset0:14 offset1:15
	ds_read2st64_b32 v[102:103], v24 offset0:16 offset1:17
	ds_read2st64_b32 v[104:105], v24 offset0:18 offset1:19
	ds_read2st64_b32 v[106:107], v24 offset0:20 offset1:21
	ds_read2st64_b32 v[108:109], v24 offset0:22 offset1:23
	ds_read2st64_b32 v[110:111], v24 offset0:24 offset1:25
	ds_read2st64_b32 v[114:115], v24 offset0:26 offset1:27
	ds_read2st64_b32 v[116:117], v24 offset0:28 offset1:29
	ds_read2st64_b32 v[118:119], v24 offset0:30 offset1:31
	ds_read2st64_b32 v[120:121], v24 offset0:32 offset1:33
	ds_read2st64_b32 v[122:123], v24 offset0:34 offset1:35
	ds_read2st64_b32 v[124:125], v24 offset0:36 offset1:37
	ds_read2st64_b32 v[126:127], v24 offset0:38 offset1:39
	ds_read2st64_b32 v[132:133], v24 offset0:40 offset1:41
	ds_read2st64_b32 v[134:135], v24 offset0:42 offset1:43
	ds_read2st64_b32 v[136:137], v24 offset0:44 offset1:45
	ds_read2st64_b32 v[138:139], v24 offset0:46 offset1:47
	ds_read2st64_b32 v[140:141], v24 offset0:56 offset1:57
	ds_read2st64_b32 v[142:143], v24 offset0:58 offset1:59
	ds_read2st64_b32 v[92:93], v24 offset0:60 offset1:61
	ds_read2st64_b32 v[94:95], v24 offset0:62 offset1:63
	ds_read2st64_b32 v[144:145], v24 offset0:48 offset1:49
	ds_read2st64_b32 v[146:147], v24 offset0:50 offset1:51
	ds_read2st64_b32 v[150:151], v24 offset0:52 offset1:53
	ds_read2st64_b32 v[24:25], v24 offset0:54 offset1:55
	s_waitcnt lgkmcnt(14)
	v_pk_add_f32 v[88:89], v[88:89], v[26:27] neg_lo:[0,1] neg_hi:[0,1]
	v_lshlrev_b32_e32 v175, 2, v179
	v_pk_add_f32 v[90:91], v[90:91], v[28:29] neg_lo:[0,1] neg_hi:[0,1]
	v_pk_mul_f32 v[158:159], v[88:89], v[88:89]
	s_waitcnt lgkmcnt(5)
	v_pk_add_f32 v[16:17], v[16:17], v[92:93] neg_lo:[0,1] neg_hi:[0,1]
	s_waitcnt lgkmcnt(4)
	v_pk_add_f32 v[18:19], v[18:19], v[94:95] neg_lo:[0,1] neg_hi:[0,1]
	global_load_dwordx4 v[92:95], v175, s[70:71]
	global_load_dwordx4 v[198:201], v175, s[70:71] offset:32
	global_load_dwordx4 v[202:205], v175, s[70:71] offset:64
	global_load_dwordx4 v[206:209], v175, s[70:71] offset:96
	global_load_dwordx4 v[210:213], v175, s[70:71] offset:128
	global_load_dwordx4 v[214:217], v175, s[70:71] offset:160
	global_load_dwordx4 v[218:221], v175, s[70:71] offset:192
	global_load_dwordx4 v[222:225], v175, s[70:71] offset:224
	global_load_dwordx4 v[226:229], v175, s[70:71] offset:256
	global_load_dwordx4 v[230:233], v175, s[70:71] offset:288
	global_load_dwordx4 v[234:237], v175, s[70:71] offset:320
	global_load_dwordx4 v[238:241], v175, s[70:71] offset:352
	global_load_dwordx4 v[242:245], v175, s[70:71] offset:384
	global_load_dwordx4 v[246:249], v175, s[70:71] offset:416
	global_load_dwordx4 v[184:187], v175, s[70:71] offset:448
	global_load_dwordx4 v[128:131], v175, s[70:71] offset:480
	v_pk_mul_f32 v[156:157], v[90:91], v[90:91]
	v_pk_add_f32 v[22:23], v[22:23], v[142:143] neg_lo:[0,1] neg_hi:[0,1]
	v_add_f32_e32 v142, v158, v159
	v_pk_add_f32 v[82:83], v[82:83], v[30:31] neg_lo:[0,1] neg_hi:[0,1]
	v_add_f32_e32 v142, v142, v156
	v_pk_mul_f32 v[162:163], v[82:83], v[82:83]
	v_add_f32_e32 v142, v142, v157
	v_pk_add_f32 v[86:87], v[86:87], v[46:47] neg_lo:[0,1] neg_hi:[0,1]
	v_add_f32_e32 v142, v142, v162
	v_pk_mul_f32 v[160:161], v[86:87], v[86:87]
	v_add_f32_e32 v142, v142, v163
	v_pk_add_f32 v[62:63], v[80:81], v[62:63] neg_lo:[0,1] neg_hi:[0,1]
	v_add_f32_e32 v142, v142, v160
	v_pk_mul_f32 v[80:81], v[62:63], v[62:63]
	v_add_f32_e32 v142, v142, v161
	v_pk_add_f32 v[84:85], v[84:85], v[96:97] neg_lo:[0,1] neg_hi:[0,1]
	v_add_f32_e32 v80, v142, v80
	v_pk_mul_f32 v[96:97], v[84:85], v[84:85]
	v_add_f32_e32 v80, v80, v81
	v_pk_add_f32 v[72:73], v[72:73], v[98:99] neg_lo:[0,1] neg_hi:[0,1]
	v_add_f32_e32 v80, v80, v96
	v_pk_mul_f32 v[98:99], v[72:73], v[72:73]
	v_add_f32_e32 v80, v80, v97
	v_pk_add_f32 v[78:79], v[78:79], v[100:101] neg_lo:[0,1] neg_hi:[0,1]
	v_add_f32_e32 v80, v80, v98
	v_pk_mul_f32 v[100:101], v[78:79], v[78:79]
	v_add_f32_e32 v80, v80, v99
	v_pk_add_f32 v[68:69], v[68:69], v[102:103] neg_lo:[0,1] neg_hi:[0,1]
	v_add_f32_e32 v80, v80, v100
	v_pk_mul_f32 v[102:103], v[68:69], v[68:69]
	v_add_f32_e32 v80, v80, v101
	v_pk_add_f32 v[76:77], v[76:77], v[104:105] neg_lo:[0,1] neg_hi:[0,1]
	v_add_f32_e32 v80, v80, v102
	v_pk_mul_f32 v[104:105], v[76:77], v[76:77]
	v_add_f32_e32 v80, v80, v103
	v_pk_add_f32 v[66:67], v[66:67], v[106:107] neg_lo:[0,1] neg_hi:[0,1]
	v_add_f32_e32 v80, v80, v104
	v_pk_mul_f32 v[106:107], v[66:67], v[66:67]
	v_add_f32_e32 v80, v80, v105
	v_pk_add_f32 v[74:75], v[74:75], v[108:109] neg_lo:[0,1] neg_hi:[0,1]
	v_add_f32_e32 v80, v80, v106
	v_pk_mul_f32 v[108:109], v[74:75], v[74:75]
	v_add_f32_e32 v80, v80, v107
	v_pk_add_f32 v[64:65], v[64:65], v[110:111] neg_lo:[0,1] neg_hi:[0,1]
	v_add_f32_e32 v80, v80, v108
	v_pk_mul_f32 v[110:111], v[64:65], v[64:65]
	v_add_f32_e32 v80, v80, v109
	v_pk_add_f32 v[70:71], v[70:71], v[114:115] neg_lo:[0,1] neg_hi:[0,1]
	v_add_f32_e32 v80, v80, v110
	v_pk_mul_f32 v[114:115], v[70:71], v[70:71]
	v_add_f32_e32 v80, v80, v111
	v_pk_add_f32 v[54:55], v[54:55], v[116:117] neg_lo:[0,1] neg_hi:[0,1]
	v_add_f32_e32 v80, v80, v114
	v_pk_mul_f32 v[116:117], v[54:55], v[54:55]
	v_add_f32_e32 v80, v80, v115
	v_pk_add_f32 v[60:61], v[60:61], v[118:119] neg_lo:[0,1] neg_hi:[0,1]
	v_add_f32_e32 v80, v80, v116
	v_pk_mul_f32 v[118:119], v[60:61], v[60:61]
	v_add_f32_e32 v80, v80, v117
	v_pk_add_f32 v[50:51], v[50:51], v[120:121] neg_lo:[0,1] neg_hi:[0,1]
	v_add_f32_e32 v80, v80, v118
	v_pk_mul_f32 v[120:121], v[50:51], v[50:51]
	v_add_f32_e32 v80, v80, v119
	v_pk_add_f32 v[58:59], v[58:59], v[122:123] neg_lo:[0,1] neg_hi:[0,1]
	v_add_f32_e32 v80, v80, v120
	v_pk_mul_f32 v[122:123], v[58:59], v[58:59]
	v_add_f32_e32 v80, v80, v121
	v_pk_add_f32 v[48:49], v[48:49], v[124:125] neg_lo:[0,1] neg_hi:[0,1]
	v_add_f32_e32 v80, v80, v122
	v_pk_mul_f32 v[124:125], v[48:49], v[48:49]
	v_add_f32_e32 v80, v80, v123
	v_pk_add_f32 v[56:57], v[56:57], v[126:127] neg_lo:[0,1] neg_hi:[0,1]
	v_add_f32_e32 v80, v80, v124
	v_pk_mul_f32 v[126:127], v[56:57], v[56:57]
	v_add_f32_e32 v80, v80, v125
	v_pk_add_f32 v[132:133], v[40:41], v[132:133] neg_lo:[0,1] neg_hi:[0,1]
	v_add_f32_e32 v80, v80, v126
	v_pk_mul_f32 v[40:41], v[132:133], v[132:133]
	v_add_f32_e32 v80, v80, v127
	v_pk_add_f32 v[46:47], v[52:53], v[134:135] neg_lo:[0,1] neg_hi:[0,1]
	v_add_f32_e32 v40, v80, v40
	v_pk_mul_f32 v[52:53], v[46:47], v[46:47]
	v_add_f32_e32 v40, v40, v41
	v_pk_add_f32 v[36:37], v[36:37], v[136:137] neg_lo:[0,1] neg_hi:[0,1]
	v_add_f32_e32 v40, v40, v52
	v_pk_mul_f32 v[134:135], v[36:37], v[36:37]
	v_add_f32_e32 v40, v40, v53
	v_pk_add_f32 v[30:31], v[44:45], v[138:139] neg_lo:[0,1] neg_hi:[0,1]
	v_add_f32_e32 v40, v40, v134
	v_pk_mul_f32 v[44:45], v[30:31], v[30:31]
	v_add_f32_e32 v40, v40, v135
	s_waitcnt lgkmcnt(3)
	v_pk_add_f32 v[34:35], v[34:35], v[144:145] neg_lo:[0,1] neg_hi:[0,1]
	v_add_f32_e32 v40, v40, v44
	v_pk_mul_f32 v[136:137], v[34:35], v[34:35]
	v_add_f32_e32 v40, v40, v45
	s_waitcnt lgkmcnt(2)
	v_pk_add_f32 v[26:27], v[42:43], v[146:147] neg_lo:[0,1] neg_hi:[0,1]
	v_add_f32_e32 v40, v40, v136
	v_pk_mul_f32 v[42:43], v[26:27], v[26:27]
	v_add_f32_e32 v40, v40, v137
	s_waitcnt lgkmcnt(1)
	v_pk_add_f32 v[28:29], v[32:33], v[150:151] neg_lo:[0,1] neg_hi:[0,1]
	v_add_f32_e32 v40, v40, v42
	v_pk_mul_f32 v[32:33], v[28:29], v[28:29]
	v_add_f32_e32 v40, v40, v43
	s_waitcnt lgkmcnt(0)
	v_pk_add_f32 v[24:25], v[38:39], v[24:25] neg_lo:[0,1] neg_hi:[0,1]
	v_add_f32_e32 v32, v40, v32
	v_pk_mul_f32 v[38:39], v[24:25], v[24:25]
	v_add_f32_e32 v32, v32, v33
	v_pk_add_f32 v[20:21], v[20:21], v[140:141] neg_lo:[0,1] neg_hi:[0,1]
	v_add_f32_e32 v32, v32, v38
	v_pk_mul_f32 v[140:141], v[20:21], v[20:21]
	v_add_f32_e32 v32, v32, v39
	v_add_f32_e32 v32, v32, v140
	v_pk_mul_f32 v[138:139], v[22:23], v[22:23]
	v_add_f32_e32 v32, v32, v141
	v_add_f32_e32 v32, v32, v138
	v_pk_mul_f32 v[152:153], v[16:17], v[16:17]
	v_add_f32_e32 v32, v32, v139
	v_add_f32_e32 v32, v32, v152
	v_pk_mul_f32 v[154:155], v[18:19], v[18:19]
	v_add_f32_e32 v32, v32, v153
	v_add_f32_e32 v32, v32, v154
	v_add_f32_e32 v38, v32, v155
	ds_bpermute_b32 v39, v195, v38
	v_lshlrev_b64 v[32:33], 11, v[176:177]
	v_lshl_add_u64 v[32:33], s[74:75], 0, v[32:33]
	v_lshl_add_u64 v[32:33], v[32:33], 0, s[12:13]
	v_lshlrev_b32_e32 v166, 1, v179
	s_waitcnt lgkmcnt(0)
	v_add_f32_e32 v38, v38, v39
	v_fmamk_f32 v38, v38, 0x3c000000, v193
	v_mul_f32_e32 v39, 0x4b800000, v38
	v_cmp_gt_f32_e32 vcc, s27, v38
	v_lshl_add_u64 v[32:33], v[32:33], 0, v[166:167]
	v_lshl_add_u64 v[44:45], v[32:33], 0, s[14:15]
	v_cndmask_b32_e32 v38, v38, v39, vcc
	v_rsq_f32_e32 v38, v38
	s_nop 0
	v_mul_f32_e32 v39, 0x45800000, v38
	v_cndmask_b32_e32 v38, v38, v39, vcc
	v_mul_f32_e32 v42, 0x3f4ccccd, v38
	v_pk_mul_f32 v[38:39], v[88:89], v[42:43] op_sel_hi:[1,0]
	v_pk_mul_f32 v[40:41], v[90:91], v[42:43] op_sel_hi:[1,0]
	s_waitcnt vmcnt(0)
	v_pk_mul_f32 v[38:39], v[92:93], v[38:39]
	v_pk_mul_f32 v[40:41], v[94:95], v[40:41]
	v_cvt_pk_bf16_f32 v92, v38, v39
	v_cvt_pk_bf16_f32 v93, v40, v41
	v_and_b32_e32 v112, 32, v190
	v_lshrrev_b32_e32 v112, 2, v112
	v_mov_b32_e32 v113, 0
	v_pk_mul_f32 v[52:53], v[84:85], v[42:43] op_sel_hi:[1,0]
	s_nop 0
	v_lshl_add_u64 v[40:41], v[44:45], 0, v[112:113]
	v_pk_mul_f32 v[32:33], v[82:83], v[42:43] op_sel_hi:[1,0]
	v_pk_mul_f32 v[46:47], v[46:47], v[42:43] op_sel_hi:[1,0]
	v_pk_mul_f32 v[30:31], v[30:31], v[42:43] op_sel_hi:[1,0]
	v_pk_mul_f32 v[34:35], v[34:35], v[42:43] op_sel_hi:[1,0]
	v_pk_mul_f32 v[26:27], v[26:27], v[42:43] op_sel_hi:[1,0]
	v_pk_mul_f32 v[24:25], v[24:25], v[42:43] op_sel_hi:[1,0]
	v_pk_mul_f32 v[20:21], v[20:21], v[42:43] op_sel_hi:[1,0]
	v_pk_mul_f32 v[22:23], v[22:23], v[42:43] op_sel_hi:[1,0]
	v_pk_mul_f32 v[16:17], v[16:17], v[42:43] op_sel_hi:[1,0]
	v_pk_mul_f32 v[18:19], v[18:19], v[42:43] op_sel_hi:[1,0]
	v_pk_mul_f32 v[32:33], v[198:199], v[32:33]
	v_pk_mul_f32 v[38:39], v[86:87], v[42:43] op_sel_hi:[1,0]
	v_cvt_pk_bf16_f32 v94, v32, v33
	v_pk_mul_f32 v[38:39], v[200:201], v[38:39]
	s_nop 0
	v_cvt_pk_bf16_f32 v95, v38, v39
	s_nop 1
	v_permlane32_swap_b32_e32 v92, v94
	v_permlane32_swap_b32_e32 v93, v95
	global_store_dwordx4 v[40:41], v[92:95], off
	v_pk_mul_f32 v[32:33], v[62:63], v[42:43] op_sel_hi:[1,0]
	v_pk_mul_f32 v[32:33], v[202:203], v[32:33]
	v_pk_mul_f32 v[38:39], v[204:205], v[52:53]
	v_cvt_pk_bf16_f32 v202, v32, v33
	v_cvt_pk_bf16_f32 v203, v38, v39
	v_pk_mul_f32 v[32:33], v[72:73], v[42:43] op_sel_hi:[1,0]
	v_pk_mul_f32 v[52:53], v[78:79], v[42:43] op_sel_hi:[1,0]
	v_pk_mul_f32 v[32:33], v[206:207], v[32:33]
	v_pk_mul_f32 v[38:39], v[208:209], v[52:53]
	v_cvt_pk_bf16_f32 v204, v32, v33
	v_cvt_pk_bf16_f32 v205, v38, v39
	s_nop 1
	v_permlane32_swap_b32_e32 v202, v204
	v_permlane32_swap_b32_e32 v203, v205
	global_store_dwordx4 v[40:41], v[202:205], off offset:32
	v_pk_mul_f32 v[32:33], v[68:69], v[42:43] op_sel_hi:[1,0]
	v_pk_mul_f32 v[52:53], v[76:77], v[42:43] op_sel_hi:[1,0]
	v_pk_mul_f32 v[32:33], v[210:211], v[32:33]
	v_pk_mul_f32 v[38:39], v[212:213], v[52:53]
	v_cvt_pk_bf16_f32 v210, v32, v33
	v_cvt_pk_bf16_f32 v211, v38, v39
	v_pk_mul_f32 v[32:33], v[66:67], v[42:43] op_sel_hi:[1,0]
	v_pk_mul_f32 v[52:53], v[74:75], v[42:43] op_sel_hi:[1,0]
	v_pk_mul_f32 v[32:33], v[214:215], v[32:33]
	v_pk_mul_f32 v[38:39], v[216:217], v[52:53]
	v_cvt_pk_bf16_f32 v212, v32, v33
	v_cvt_pk_bf16_f32 v213, v38, v39
	s_nop 1
	v_permlane32_swap_b32_e32 v210, v212
	v_permlane32_swap_b32_e32 v211, v213
	global_store_dwordx4 v[40:41], v[210:213], off offset:64
	v_pk_mul_f32 v[32:33], v[64:65], v[42:43] op_sel_hi:[1,0]
	v_pk_mul_f32 v[52:53], v[70:71], v[42:43] op_sel_hi:[1,0]
	v_pk_mul_f32 v[32:33], v[32:33], v[218:219]
	v_pk_mul_f32 v[38:39], v[52:53], v[220:221]
	v_cvt_pk_bf16_f32 v218, v32, v33
	v_cvt_pk_bf16_f32 v219, v38, v39
	v_pk_mul_f32 v[32:33], v[54:55], v[42:43] op_sel_hi:[1,0]
	v_pk_mul_f32 v[52:53], v[60:61], v[42:43] op_sel_hi:[1,0]
	v_pk_mul_f32 v[32:33], v[32:33], v[222:223]
	v_pk_mul_f32 v[38:39], v[52:53], v[224:225]
	v_cvt_pk_bf16_f32 v220, v32, v33
	v_cvt_pk_bf16_f32 v221, v38, v39
	s_nop 1
	v_permlane32_swap_b32_e32 v218, v220
	v_permlane32_swap_b32_e32 v219, v221
	global_store_dwordx4 v[40:41], v[218:221], off offset:96
	v_pk_mul_f32 v[32:33], v[50:51], v[42:43] op_sel_hi:[1,0]
	v_pk_mul_f32 v[50:51], v[58:59], v[42:43] op_sel_hi:[1,0]
	v_pk_mul_f32 v[32:33], v[32:33], v[226:227]
	v_pk_mul_f32 v[38:39], v[50:51], v[228:229]
	v_cvt_pk_bf16_f32 v226, v32, v33
	v_cvt_pk_bf16_f32 v227, v38, v39
	v_pk_mul_f32 v[32:33], v[48:49], v[42:43] op_sel_hi:[1,0]
	v_pk_mul_f32 v[48:49], v[56:57], v[42:43] op_sel_hi:[1,0]
	v_pk_mul_f32 v[32:33], v[32:33], v[230:231]
	v_pk_mul_f32 v[38:39], v[48:49], v[232:233]
	v_cvt_pk_bf16_f32 v228, v32, v33
	v_cvt_pk_bf16_f32 v229, v38, v39
	s_nop 1
	v_permlane32_swap_b32_e32 v226, v228
	v_permlane32_swap_b32_e32 v227, v229
	global_store_dwordx4 v[40:41], v[226:229], off offset:128
	v_pk_mul_f32 v[32:33], v[132:133], v[42:43] op_sel_hi:[1,0]
	v_pk_mul_f32 v[32:33], v[32:33], v[234:235]
	v_pk_mul_f32 v[38:39], v[46:47], v[236:237]
	v_cvt_pk_bf16_f32 v234, v32, v33
	v_cvt_pk_bf16_f32 v235, v38, v39
	v_pk_mul_f32 v[32:33], v[36:37], v[42:43] op_sel_hi:[1,0]
	v_pk_mul_f32 v[30:31], v[30:31], v[240:241]
	v_pk_mul_f32 v[32:33], v[32:33], v[238:239]
	s_nop 0
	v_cvt_pk_bf16_f32 v236, v32, v33
	v_cvt_pk_bf16_f32 v237, v30, v31
	s_nop 1
	v_permlane32_swap_b32_e32 v234, v236
	v_permlane32_swap_b32_e32 v235, v237
	global_store_dwordx4 v[40:41], v[234:237], off offset:160
	v_pk_mul_f32 v[30:31], v[34:35], v[242:243]
	v_pk_mul_f32 v[26:27], v[26:27], v[244:245]
	v_cvt_pk_bf16_f32 v242, v30, v31
	v_cvt_pk_bf16_f32 v243, v26, v27
	v_pk_mul_f32 v[26:27], v[28:29], v[42:43] op_sel_hi:[1,0]
	v_pk_mul_f32 v[24:25], v[24:25], v[248:249]
	v_pk_mul_f32 v[26:27], v[26:27], v[246:247]
	s_nop 0
	v_cvt_pk_bf16_f32 v244, v26, v27
	v_cvt_pk_bf16_f32 v245, v24, v25
	s_nop 1
	v_permlane32_swap_b32_e32 v242, v244
	v_permlane32_swap_b32_e32 v243, v245
	global_store_dwordx4 v[40:41], v[242:245], off offset:192
	v_pk_mul_f32 v[20:21], v[20:21], v[184:185]
	v_pk_mul_f32 v[22:23], v[22:23], v[186:187]
	v_cvt_pk_bf16_f32 v184, v20, v21
	v_cvt_pk_bf16_f32 v185, v22, v23
	v_pk_mul_f32 v[16:17], v[16:17], v[128:129]
	v_pk_mul_f32 v[18:19], v[18:19], v[130:131]
	v_cvt_pk_bf16_f32 v186, v16, v17
	v_cvt_pk_bf16_f32 v187, v18, v19
	s_nop 1
	v_permlane32_swap_b32_e32 v184, v186
	v_permlane32_swap_b32_e32 v185, v187
	global_store_dwordx4 v[40:41], v[184:187], off offset:224
	s_branch .LBB0_427
